# attention tiles: last softmax group and last PV k-step deferred past the tile barrier into the next tile's first QK MFMA gaps
# baseline (speedup 1.0000x reference)
.Lu883:
	s_add_i32 s57, s57, 2
	s_add_u32 s8, s8, 0xc000
	s_addc_u32 s9, s9, 0
	s_and_b64 vcc, exec, s[12:13]
	s_waitcnt vmcnt(0) lgkmcnt(0)
	s_barrier
	s_cbranch_vccnz .Lu_exit
	s_add_u32 s72, s8, s0
	s_addc_u32 s73, s9, s1
	s_add_u32 m0, s74, 0x6000
	s_nop 0
	global_load_lds_dwordx4 v164, s[72:73]
	s_add_u32 m0, s74, 0x8000
	s_nop 0
	global_load_lds_dwordx4 v170, s[72:73]
	s_add_u32 m0, s74, 0xa000
	s_nop 0
	global_load_lds_dwordx4 v168, s[72:73]
	s_cmp_gt_u32 s57, s75
	s_cbranch_scc1 .Lu_pb_only
	ds_read_b128 v[146:149], v198
	ds_read_b128 v[150:153], v171
	ds_read_b128 v[246:249], v174
	ds_read_b128 v[250:253], v175
	ds_read_b128 v[180:183], v176
	ds_read_b128 v[184:187], v177
	s_waitcnt lgkmcnt(5)
	v_mfma_f32_32x32x16_bf16 v[82:97], v[146:149], v[98:101], v[210:225]
	ds_read_b128 v[146:149], v178
	v_exp_f32_e32 v74, v74
	v_exp_f32_e32 v75, v75
	v_exp_f32_e32 v76, v76
	s_waitcnt lgkmcnt(5)
	v_mfma_f32_32x32x16_bf16 v[82:97], v[150:153], v[102:105], v[82:97]
	ds_read_b128 v[150:153], v179
	v_add_f32_e32 v173, v173, v74
	v_exp_f32_e32 v77, v77
	v_add_f32_e32 v242, v242, v75
	s_waitcnt lgkmcnt(5)
	v_mfma_f32_32x32x16_bf16 v[82:97], v[246:249], v[106:109], v[82:97]
	ds_read_b128 v[246:249], v199
	v_cvt_pk_bf16_f32 v74, v74, v75
	v_exp_f32_e32 v78, v78
	v_add_f32_e32 v173, v173, v76
	s_waitcnt lgkmcnt(5)
	v_mfma_f32_32x32x16_bf16 v[82:97], v[250:253], v[110:113], v[82:97]
	ds_read_b128 v[250:253], v202
	v_exp_f32_e32 v79, v79
	v_add_f32_e32 v242, v242, v77
	v_cvt_pk_bf16_f32 v75, v76, v77
	s_waitcnt lgkmcnt(5)
	v_mfma_f32_32x32x16_bf16 v[82:97], v[180:183], v[122:125], v[82:97]
	ds_read_b128 v[180:183], v207
	v_exp_f32_e32 v80, v80
	v_add_f32_e32 v173, v173, v78
	v_exp_f32_e32 v81, v81
	s_waitcnt lgkmcnt(5)
	v_mfma_f32_32x32x16_bf16 v[82:97], v[184:187], v[114:117], v[82:97]
	ds_read_b128 v[184:187], v208
	v_add_f32_e32 v242, v242, v79
	v_cvt_pk_bf16_f32 v76, v78, v79
	v_add_f32_e32 v173, v173, v80
	s_waitcnt lgkmcnt(5)
	v_mfma_f32_32x32x16_bf16 v[82:97], v[146:149], v[118:121], v[82:97]
	ds_read_b128 v[146:149], v198 offset:8192
	v_add_f32_e32 v242, v242, v81
	v_cvt_pk_bf16_f32 v77, v80, v81
	v_add_f32_e32 v173, v173, v242
	s_waitcnt lgkmcnt(5)
	v_mfma_f32_32x32x16_bf16 v[82:97], v[150:153], v[126:129], v[82:97]
	ds_read_b128 v[150:153], v171 offset:8192
	s_waitcnt lgkmcnt(5)
	v_mfma_f32_32x32x16_bf16 v[82:97], v[246:249], v[130:133], v[82:97]
	ds_read_b128 v[246:249], v174 offset:8192
	v_mfma_f32_32x32x16_bf16 v[50:65], v[238:241], v[74:77], v[50:65]
	s_waitcnt lgkmcnt(5)
	v_mfma_f32_32x32x16_bf16 v[82:97], v[250:253], v[134:137], v[82:97]
	ds_read_b128 v[250:253], v175 offset:8192
	v_mfma_f32_32x32x16_bf16 v[34:49], v[234:237], v[74:77], v[34:49]
	s_waitcnt lgkmcnt(5)
	v_mfma_f32_32x32x16_bf16 v[82:97], v[180:183], v[138:141], v[82:97]
	ds_read_b128 v[180:183], v176 offset:8192
	v_mfma_f32_32x32x16_bf16 v[18:33], v[230:233], v[74:77], v[18:33]
	s_waitcnt lgkmcnt(5)
	v_mfma_f32_32x32x16_bf16 v[82:97], v[184:187], v[142:145], v[82:97]
	ds_read_b128 v[184:187], v177 offset:8192
	v_mfma_f32_32x32x16_bf16 v[2:17], v[226:229], v[74:77], v[2:17]
	ds_read_b64_tr_b16 v[158:159], v188 offset:0
	ds_read_b64_tr_b16 v[160:161], v189 offset:0
	s_waitcnt lgkmcnt(7)
	v_mfma_f32_32x32x16_bf16 v[66:81], v[146:149], v[98:101], v[210:225]
	ds_read_b128 v[146:149], v178 offset:8192
	ds_read_b64_tr_b16 v[154:155], v192 offset:0
	ds_read_b64_tr_b16 v[156:157], v193 offset:0
	s_waitcnt lgkmcnt(9)
	v_mfma_f32_32x32x16_bf16 v[66:81], v[150:153], v[102:105], v[66:81]
	ds_read_b128 v[150:153], v179 offset:8192
	s_waitcnt lgkmcnt(9)
	v_mfma_f32_32x32x16_bf16 v[66:81], v[246:249], v[106:109], v[66:81]
	ds_read_b128 v[246:249], v199 offset:4096
	v_exp_f32_e32 v82, v82
	v_exp_f32_e32 v83, v83
	v_exp_f32_e32 v84, v84
	v_add_f32_e32 v173, v173, v82
	s_waitcnt lgkmcnt(9)
	v_mfma_f32_32x32x16_bf16 v[66:81], v[250:253], v[110:113], v[66:81]
	ds_read_b128 v[250:253], v202 offset:4096
	v_exp_f32_e32 v85, v85
	v_mov_b32_e32 v242, v83
	v_cvt_pk_bf16_f32 v82, v82, v83
	v_exp_f32_e32 v86, v86
	s_waitcnt lgkmcnt(9)
	v_mfma_f32_32x32x16_bf16 v[66:81], v[180:183], v[122:125], v[66:81]
	ds_read_b128 v[180:183], v207 offset:4096
	v_add_f32_e32 v173, v173, v84
	v_exp_f32_e32 v87, v87
	v_add_f32_e32 v242, v242, v85
	v_cvt_pk_bf16_f32 v83, v84, v85
	s_waitcnt lgkmcnt(9)
	v_mfma_f32_32x32x16_bf16 v[66:81], v[184:187], v[114:117], v[66:81]
	ds_read_b128 v[184:187], v208 offset:4096
	ds_read_b64_tr_b16 v[238:239], v188 offset:0x1000
	ds_read_b64_tr_b16 v[240:241], v189 offset:0x1000
	v_exp_f32_e32 v88, v88
	v_add_f32_e32 v173, v173, v86
	v_exp_f32_e32 v89, v89
	v_add_f32_e32 v242, v242, v87
	s_waitcnt lgkmcnt(9)
	v_mfma_f32_32x32x16_bf16 v[66:81], v[146:149], v[118:121], v[66:81]
	ds_read_b64_tr_b16 v[234:235], v192 offset:0x1000
	ds_read_b64_tr_b16 v[236:237], v193 offset:0x1000
	v_cvt_pk_bf16_f32 v84, v86, v87
	v_add_f32_e32 v173, v173, v88
	v_add_f32_e32 v242, v242, v89
	v_cvt_pk_bf16_f32 v85, v88, v89
	s_waitcnt lgkmcnt(8)
	v_mfma_f32_32x32x16_bf16 v[66:81], v[150:153], v[126:129], v[66:81]
	ds_read_b64_tr_b16 v[230:231], v194 offset:0x1000
	ds_read_b64_tr_b16 v[232:233], v195 offset:0x1000
	ds_read_b64_tr_b16 v[150:151], v194 offset:0
	ds_read_b64_tr_b16 v[152:153], v195 offset:0
	ds_read_b64_tr_b16 v[146:147], v196 offset:0
	ds_read_b64_tr_b16 v[148:149], v197 offset:0
	v_exp_f32_e32 v90, v90
	v_exp_f32_e32 v91, v91
	v_exp_f32_e32 v92, v92
	v_add_f32_e32 v173, v173, v90
	s_waitcnt lgkmcnt(13)
	v_mfma_f32_32x32x16_bf16 v[66:81], v[246:249], v[130:133], v[66:81]
	ds_read_b64_tr_b16 v[226:227], v196 offset:0x1000
	ds_read_b64_tr_b16 v[228:229], v197 offset:0x1000
	v_exp_f32_e32 v93, v93
	v_add_f32_e32 v242, v242, v91
	v_cvt_pk_bf16_f32 v90, v90, v91
	v_exp_f32_e32 v94, v94
	s_waitcnt lgkmcnt(14)
	v_mfma_f32_32x32x16_bf16 v[66:81], v[250:253], v[134:137], v[66:81]
	v_add_f32_e32 v173, v173, v92
	v_exp_f32_e32 v95, v95
	v_add_f32_e32 v242, v242, v93
	v_cvt_pk_bf16_f32 v91, v92, v93
	s_waitcnt lgkmcnt(13)
	v_mfma_f32_32x32x16_bf16 v[66:81], v[180:183], v[138:141], v[66:81]
	v_exp_f32_e32 v96, v96
	v_add_f32_e32 v173, v173, v94
	v_exp_f32_e32 v97, v97
	v_add_f32_e32 v242, v242, v95
	s_waitcnt lgkmcnt(12)
	v_mfma_f32_32x32x16_bf16 v[66:81], v[184:187], v[142:145], v[66:81]
	v_cvt_pk_bf16_f32 v92, v94, v95
	v_add_f32_e32 v173, v173, v96
	v_add_f32_e32 v242, v242, v97
	v_cvt_pk_bf16_f32 v93, v96, v97
	s_waitcnt lgkmcnt(2)
	v_mfma_f32_32x32x16_bf16 v[50:65], v[158:161], v[82:85], v[50:65]
	ds_read_b64_tr_b16 v[158:159], v188 offset:0x2000
	ds_read_b64_tr_b16 v[160:161], v189 offset:0x2000
	v_mfma_f32_32x32x16_bf16 v[34:49], v[154:157], v[82:85], v[34:49]
	ds_read_b64_tr_b16 v[154:155], v192 offset:0x2000
	ds_read_b64_tr_b16 v[156:157], v193 offset:0x2000
	v_mfma_f32_32x32x16_bf16 v[18:33], v[150:153], v[82:85], v[18:33]
	ds_read_b64_tr_b16 v[150:151], v194 offset:0x2000
	ds_read_b64_tr_b16 v[152:153], v195 offset:0x2000
	v_mfma_f32_32x32x16_bf16 v[2:17], v[146:149], v[82:85], v[2:17]
	v_exp_f32_e32 v66, v66
	v_exp_f32_e32 v67, v67
	v_exp_f32_e32 v68, v68
	v_add_f32_e32 v173, v173, v66
	ds_read_b64_tr_b16 v[146:147], v196 offset:0x2000
	ds_read_b64_tr_b16 v[148:149], v197 offset:0x2000
	s_waitcnt lgkmcnt(8)
	v_mfma_f32_32x32x16_bf16 v[50:65], v[238:241], v[90:93], v[50:65]
	v_exp_f32_e32 v69, v69
	v_add_f32_e32 v242, v242, v67
	v_cvt_pk_bf16_f32 v66, v66, v67
	v_exp_f32_e32 v70, v70
	ds_read_b64_tr_b16 v[238:239], v188 offset:0x3000
	ds_read_b64_tr_b16 v[240:241], v189 offset:0x3000
	v_mfma_f32_32x32x16_bf16 v[34:49], v[234:237], v[90:93], v[34:49]
	v_add_f32_e32 v173, v173, v68
	v_exp_f32_e32 v71, v71
	v_add_f32_e32 v242, v242, v69
	v_cvt_pk_bf16_f32 v67, v68, v69
	ds_read_b64_tr_b16 v[234:235], v192 offset:0x3000
	ds_read_b64_tr_b16 v[236:237], v193 offset:0x3000
	v_mfma_f32_32x32x16_bf16 v[18:33], v[230:233], v[90:93], v[18:33]
	v_exp_f32_e32 v72, v72
	v_add_f32_e32 v173, v173, v70
	v_exp_f32_e32 v73, v73
	v_add_f32_e32 v242, v242, v71
	ds_read_b64_tr_b16 v[230:231], v194 offset:0x3000
	ds_read_b64_tr_b16 v[232:233], v195 offset:0x3000
	v_mfma_f32_32x32x16_bf16 v[2:17], v[226:229], v[90:93], v[2:17]
	v_cvt_pk_bf16_f32 v68, v70, v71
	v_add_f32_e32 v173, v173, v72
	v_add_f32_e32 v242, v242, v73
	v_cvt_pk_bf16_f32 v69, v72, v73
	ds_read_b64_tr_b16 v[226:227], v196 offset:0x3000
	ds_read_b64_tr_b16 v[228:229], v197 offset:0x3000
	s_waitcnt lgkmcnt(8)
	v_mfma_f32_32x32x16_bf16 v[50:65], v[158:161], v[66:69], v[50:65]
	v_mfma_f32_32x32x16_bf16 v[34:49], v[154:157], v[66:69], v[34:49]
	v_mfma_f32_32x32x16_bf16 v[18:33], v[150:153], v[66:69], v[18:33]
	v_mfma_f32_32x32x16_bf16 v[2:17], v[146:149], v[66:69], v[2:17]
	s_branch .Lu888
.Lu_pb_only:
	s_add_i32 s98, s75, 1
	s_cmp_lg_u32 s57, s98
	s_cbranch_scc1 .Lu888
	v_exp_f32_e32 v74, v74
	v_exp_f32_e32 v75, v75
	v_exp_f32_e32 v76, v76
	v_add_f32_e32 v173, v173, v74
	v_exp_f32_e32 v77, v77
	v_add_f32_e32 v242, v242, v75
	v_cvt_pk_bf16_f32 v74, v74, v75
	v_exp_f32_e32 v78, v78
	v_add_f32_e32 v173, v173, v76
	v_exp_f32_e32 v79, v79
	v_add_f32_e32 v242, v242, v77
	v_cvt_pk_bf16_f32 v75, v76, v77
	v_exp_f32_e32 v80, v80
	v_add_f32_e32 v173, v173, v78
	v_exp_f32_e32 v81, v81
	v_add_f32_e32 v242, v242, v79
	v_cvt_pk_bf16_f32 v76, v78, v79
	v_add_f32_e32 v173, v173, v80
	v_add_f32_e32 v242, v242, v81
	v_cvt_pk_bf16_f32 v77, v80, v81
	v_add_f32_e32 v173, v173, v242
	s_nop 0
	v_mfma_f32_32x32x16_bf16 v[50:65], v[238:241], v[74:77], v[50:65]
	v_mfma_f32_32x32x16_bf16 v[34:49], v[234:237], v[74:77], v[34:49]
	v_mfma_f32_32x32x16_bf16 v[18:33], v[230:233], v[74:77], v[18:33]
	v_mfma_f32_32x32x16_bf16 v[2:17], v[226:229], v[74:77], v[2:17]
	s_branch .Lu888
.Lu884:
	s_add_u32 s72, s8, s0
	s_addc_u32 s73, s9, s1
	s_add_u32 m0, s74, 0x6000
	s_nop 0
	global_load_lds_dwordx4 v164, s[72:73]
	s_add_u32 m0, s74, 0x8000
	s_nop 0
	global_load_lds_dwordx4 v170, s[72:73]
	s_add_u32 m0, s74, 0xa000
	s_nop 0
	global_load_lds_dwordx4 v168, s[72:73]
	s_cmp_gt_u32 s57, s75
	s_cbranch_scc1 .Lu888
	ds_read_b128 v[146:149], v198
	ds_read_b128 v[150:153], v171
	ds_read_b128 v[246:249], v174
	ds_read_b128 v[250:253], v175
	ds_read_b128 v[180:183], v176
	ds_read_b128 v[184:187], v177
	s_waitcnt lgkmcnt(5)
	v_mfma_f32_32x32x16_bf16 v[82:97], v[146:149], v[98:101], v[210:225]
	ds_read_b128 v[146:149], v178
	s_waitcnt lgkmcnt(5)
	v_mfma_f32_32x32x16_bf16 v[82:97], v[150:153], v[102:105], v[82:97]
	ds_read_b128 v[150:153], v179
	s_waitcnt lgkmcnt(5)
	v_mfma_f32_32x32x16_bf16 v[82:97], v[246:249], v[106:109], v[82:97]
	ds_read_b128 v[246:249], v199
	s_waitcnt lgkmcnt(5)
	v_mfma_f32_32x32x16_bf16 v[82:97], v[250:253], v[110:113], v[82:97]
	ds_read_b128 v[250:253], v202
	s_waitcnt lgkmcnt(5)
	v_mfma_f32_32x32x16_bf16 v[82:97], v[180:183], v[122:125], v[82:97]
	ds_read_b128 v[180:183], v207
	s_waitcnt lgkmcnt(5)
	v_mfma_f32_32x32x16_bf16 v[82:97], v[184:187], v[114:117], v[82:97]
	ds_read_b128 v[184:187], v208
	s_waitcnt lgkmcnt(5)
	v_mfma_f32_32x32x16_bf16 v[82:97], v[146:149], v[118:121], v[82:97]
	ds_read_b128 v[146:149], v198 offset:8192
	s_waitcnt lgkmcnt(5)
	v_mfma_f32_32x32x16_bf16 v[82:97], v[150:153], v[126:129], v[82:97]
	ds_read_b128 v[150:153], v171 offset:8192
	s_waitcnt lgkmcnt(5)
	v_mfma_f32_32x32x16_bf16 v[82:97], v[246:249], v[130:133], v[82:97]
	ds_read_b128 v[246:249], v174 offset:8192
	s_waitcnt lgkmcnt(5)
	v_mfma_f32_32x32x16_bf16 v[82:97], v[250:253], v[134:137], v[82:97]
	ds_read_b128 v[250:253], v175 offset:8192
	s_waitcnt lgkmcnt(5)
	v_mfma_f32_32x32x16_bf16 v[82:97], v[180:183], v[138:141], v[82:97]
	ds_read_b128 v[180:183], v176 offset:8192
	s_waitcnt lgkmcnt(5)
	v_mfma_f32_32x32x16_bf16 v[82:97], v[184:187], v[142:145], v[82:97]
	ds_read_b128 v[184:187], v177 offset:8192
	ds_read_b64_tr_b16 v[158:159], v188 offset:0
	ds_read_b64_tr_b16 v[160:161], v189 offset:0
	s_waitcnt lgkmcnt(7)
	v_mfma_f32_32x32x16_bf16 v[66:81], v[146:149], v[98:101], v[210:225]
	ds_read_b128 v[146:149], v178 offset:8192
	ds_read_b64_tr_b16 v[154:155], v192 offset:0
	ds_read_b64_tr_b16 v[156:157], v193 offset:0
	s_waitcnt lgkmcnt(9)
	v_mfma_f32_32x32x16_bf16 v[66:81], v[150:153], v[102:105], v[66:81]
	ds_read_b128 v[150:153], v179 offset:8192
	s_waitcnt lgkmcnt(9)
	v_mfma_f32_32x32x16_bf16 v[66:81], v[246:249], v[106:109], v[66:81]
	ds_read_b128 v[246:249], v199 offset:4096
	v_exp_f32_e32 v82, v82
	v_exp_f32_e32 v83, v83
	v_exp_f32_e32 v84, v84
	v_add_f32_e32 v173, v173, v82
	s_waitcnt lgkmcnt(9)
	v_mfma_f32_32x32x16_bf16 v[66:81], v[250:253], v[110:113], v[66:81]
	ds_read_b128 v[250:253], v202 offset:4096
	v_exp_f32_e32 v85, v85
	v_mov_b32_e32 v242, v83
	v_cvt_pk_bf16_f32 v82, v82, v83
	v_exp_f32_e32 v86, v86
	s_waitcnt lgkmcnt(9)
	v_mfma_f32_32x32x16_bf16 v[66:81], v[180:183], v[122:125], v[66:81]
	ds_read_b128 v[180:183], v207 offset:4096
	v_add_f32_e32 v173, v173, v84
	v_exp_f32_e32 v87, v87
	v_add_f32_e32 v242, v242, v85
	v_cvt_pk_bf16_f32 v83, v84, v85
	s_waitcnt lgkmcnt(9)
	v_mfma_f32_32x32x16_bf16 v[66:81], v[184:187], v[114:117], v[66:81]
	ds_read_b128 v[184:187], v208 offset:4096
	ds_read_b64_tr_b16 v[238:239], v188 offset:0x1000
	ds_read_b64_tr_b16 v[240:241], v189 offset:0x1000
	v_exp_f32_e32 v88, v88
	v_add_f32_e32 v173, v173, v86
	v_exp_f32_e32 v89, v89
	v_add_f32_e32 v242, v242, v87
	s_waitcnt lgkmcnt(9)
	v_mfma_f32_32x32x16_bf16 v[66:81], v[146:149], v[118:121], v[66:81]
	ds_read_b64_tr_b16 v[234:235], v192 offset:0x1000
	ds_read_b64_tr_b16 v[236:237], v193 offset:0x1000
	v_cvt_pk_bf16_f32 v84, v86, v87
	v_add_f32_e32 v173, v173, v88
	v_add_f32_e32 v242, v242, v89
	v_cvt_pk_bf16_f32 v85, v88, v89
	s_waitcnt lgkmcnt(8)
	v_mfma_f32_32x32x16_bf16 v[66:81], v[150:153], v[126:129], v[66:81]
	ds_read_b64_tr_b16 v[230:231], v194 offset:0x1000
	ds_read_b64_tr_b16 v[232:233], v195 offset:0x1000
	ds_read_b64_tr_b16 v[150:151], v194 offset:0
	ds_read_b64_tr_b16 v[152:153], v195 offset:0
	ds_read_b64_tr_b16 v[146:147], v196 offset:0
	ds_read_b64_tr_b16 v[148:149], v197 offset:0
	v_exp_f32_e32 v90, v90
	v_exp_f32_e32 v91, v91
	v_exp_f32_e32 v92, v92
	v_add_f32_e32 v173, v173, v90
	s_waitcnt lgkmcnt(13)
	v_mfma_f32_32x32x16_bf16 v[66:81], v[246:249], v[130:133], v[66:81]
	ds_read_b64_tr_b16 v[226:227], v196 offset:0x1000
	ds_read_b64_tr_b16 v[228:229], v197 offset:0x1000
	v_exp_f32_e32 v93, v93
	v_add_f32_e32 v242, v242, v91
	v_cvt_pk_bf16_f32 v90, v90, v91
	v_exp_f32_e32 v94, v94
	s_waitcnt lgkmcnt(14)
	v_mfma_f32_32x32x16_bf16 v[66:81], v[250:253], v[134:137], v[66:81]
	v_add_f32_e32 v173, v173, v92
	v_exp_f32_e32 v95, v95
	v_add_f32_e32 v242, v242, v93
	v_cvt_pk_bf16_f32 v91, v92, v93
	s_waitcnt lgkmcnt(13)
	v_mfma_f32_32x32x16_bf16 v[66:81], v[180:183], v[138:141], v[66:81]
	v_exp_f32_e32 v96, v96
	v_add_f32_e32 v173, v173, v94
	v_exp_f32_e32 v97, v97
	v_add_f32_e32 v242, v242, v95
	s_waitcnt lgkmcnt(12)
	v_mfma_f32_32x32x16_bf16 v[66:81], v[184:187], v[142:145], v[66:81]
	v_cvt_pk_bf16_f32 v92, v94, v95
	v_add_f32_e32 v173, v173, v96
	v_add_f32_e32 v242, v242, v97
	v_cvt_pk_bf16_f32 v93, v96, v97
	s_waitcnt lgkmcnt(2)
	v_mfma_f32_32x32x16_bf16 v[50:65], v[158:161], v[82:85], v[50:65]
	ds_read_b64_tr_b16 v[158:159], v188 offset:0x2000
	ds_read_b64_tr_b16 v[160:161], v189 offset:0x2000
	v_mfma_f32_32x32x16_bf16 v[34:49], v[154:157], v[82:85], v[34:49]
	ds_read_b64_tr_b16 v[154:155], v192 offset:0x2000
	ds_read_b64_tr_b16 v[156:157], v193 offset:0x2000
	v_mfma_f32_32x32x16_bf16 v[18:33], v[150:153], v[82:85], v[18:33]
	ds_read_b64_tr_b16 v[150:151], v194 offset:0x2000
	ds_read_b64_tr_b16 v[152:153], v195 offset:0x2000
	v_mfma_f32_32x32x16_bf16 v[2:17], v[146:149], v[82:85], v[2:17]
	v_exp_f32_e32 v66, v66
	v_exp_f32_e32 v67, v67
	v_exp_f32_e32 v68, v68
	v_add_f32_e32 v173, v173, v66
	ds_read_b64_tr_b16 v[146:147], v196 offset:0x2000
	ds_read_b64_tr_b16 v[148:149], v197 offset:0x2000
	s_waitcnt lgkmcnt(8)
	v_mfma_f32_32x32x16_bf16 v[50:65], v[238:241], v[90:93], v[50:65]
	v_exp_f32_e32 v69, v69
	v_add_f32_e32 v242, v242, v67
	v_cvt_pk_bf16_f32 v66, v66, v67
	v_exp_f32_e32 v70, v70
	ds_read_b64_tr_b16 v[238:239], v188 offset:0x3000
	ds_read_b64_tr_b16 v[240:241], v189 offset:0x3000
	v_mfma_f32_32x32x16_bf16 v[34:49], v[234:237], v[90:93], v[34:49]
	v_add_f32_e32 v173, v173, v68
	v_exp_f32_e32 v71, v71
	v_add_f32_e32 v242, v242, v69
	v_cvt_pk_bf16_f32 v67, v68, v69
	ds_read_b64_tr_b16 v[234:235], v192 offset:0x3000
	ds_read_b64_tr_b16 v[236:237], v193 offset:0x3000
	v_mfma_f32_32x32x16_bf16 v[18:33], v[230:233], v[90:93], v[18:33]
	v_exp_f32_e32 v72, v72
	v_add_f32_e32 v173, v173, v70
	v_exp_f32_e32 v73, v73
	v_add_f32_e32 v242, v242, v71
	ds_read_b64_tr_b16 v[230:231], v194 offset:0x3000
	ds_read_b64_tr_b16 v[232:233], v195 offset:0x3000
	v_mfma_f32_32x32x16_bf16 v[2:17], v[226:229], v[90:93], v[2:17]
	v_cvt_pk_bf16_f32 v68, v70, v71
	v_add_f32_e32 v173, v173, v72
	v_add_f32_e32 v242, v242, v73
	v_cvt_pk_bf16_f32 v69, v72, v73
	ds_read_b64_tr_b16 v[226:227], v196 offset:0x3000
	ds_read_b64_tr_b16 v[228:229], v197 offset:0x3000
	s_waitcnt lgkmcnt(8)
	v_mfma_f32_32x32x16_bf16 v[50:65], v[158:161], v[66:69], v[50:65]
	v_mfma_f32_32x32x16_bf16 v[34:49], v[154:157], v[66:69], v[34:49]
	v_mfma_f32_32x32x16_bf16 v[18:33], v[150:153], v[66:69], v[18:33]
	v_mfma_f32_32x32x16_bf16 v[2:17], v[146:149], v[66:69], v[2:17]

.Lu890:
	s_cmp_ge_u32 s57, s75
	s_cbranch_scc1 .Lu_pa_only
	ds_read_b128 v[146:149], v198 offset:24576
	ds_read_b128 v[150:153], v171 offset:24576
	ds_read_b128 v[246:249], v174 offset:24576
	ds_read_b128 v[250:253], v175 offset:24576
	ds_read_b128 v[180:183], v176 offset:24576
	ds_read_b128 v[184:187], v177 offset:24576
	s_waitcnt lgkmcnt(5)
	v_mfma_f32_32x32x16_bf16 v[82:97], v[146:149], v[98:101], v[210:225]
	ds_read_b128 v[146:149], v178 offset:24576
	v_exp_f32_e32 v74, v74
	v_exp_f32_e32 v75, v75
	v_exp_f32_e32 v76, v76
	s_waitcnt lgkmcnt(5)
	v_mfma_f32_32x32x16_bf16 v[82:97], v[150:153], v[102:105], v[82:97]
	ds_read_b128 v[150:153], v179 offset:24576
	v_add_f32_e32 v173, v173, v74
	v_exp_f32_e32 v77, v77
	v_add_f32_e32 v242, v242, v75
	s_waitcnt lgkmcnt(5)
	v_mfma_f32_32x32x16_bf16 v[82:97], v[246:249], v[106:109], v[82:97]
	ds_read_b128 v[246:249], v199 offset:24576
	v_cvt_pk_bf16_f32 v74, v74, v75
	v_exp_f32_e32 v78, v78
	v_add_f32_e32 v173, v173, v76
	s_waitcnt lgkmcnt(5)
	v_mfma_f32_32x32x16_bf16 v[82:97], v[250:253], v[110:113], v[82:97]
	ds_read_b128 v[250:253], v202 offset:24576
	v_exp_f32_e32 v79, v79
	v_add_f32_e32 v242, v242, v77
	v_cvt_pk_bf16_f32 v75, v76, v77
	s_waitcnt lgkmcnt(5)
	v_mfma_f32_32x32x16_bf16 v[82:97], v[180:183], v[122:125], v[82:97]
	ds_read_b128 v[180:183], v207 offset:24576
	v_exp_f32_e32 v80, v80
	v_add_f32_e32 v173, v173, v78
	v_exp_f32_e32 v81, v81
	s_waitcnt lgkmcnt(5)
	v_mfma_f32_32x32x16_bf16 v[82:97], v[184:187], v[114:117], v[82:97]
	ds_read_b128 v[184:187], v208 offset:24576
	v_add_f32_e32 v242, v242, v79
	v_cvt_pk_bf16_f32 v76, v78, v79
	v_add_f32_e32 v173, v173, v80
	s_waitcnt lgkmcnt(5)
	v_mfma_f32_32x32x16_bf16 v[82:97], v[146:149], v[118:121], v[82:97]
	ds_read_b128 v[146:149], v198 offset:32768
	v_add_f32_e32 v242, v242, v81
	v_cvt_pk_bf16_f32 v77, v80, v81
	v_add_f32_e32 v173, v173, v242
	s_waitcnt lgkmcnt(5)
	v_mfma_f32_32x32x16_bf16 v[82:97], v[150:153], v[126:129], v[82:97]
	ds_read_b128 v[150:153], v171 offset:32768
	s_waitcnt lgkmcnt(5)
	v_mfma_f32_32x32x16_bf16 v[82:97], v[246:249], v[130:133], v[82:97]
	ds_read_b128 v[246:249], v174 offset:32768
	v_mfma_f32_32x32x16_bf16 v[50:65], v[238:241], v[74:77], v[50:65]
	s_waitcnt lgkmcnt(5)
	v_mfma_f32_32x32x16_bf16 v[82:97], v[250:253], v[134:137], v[82:97]
	ds_read_b128 v[250:253], v175 offset:32768
	v_mfma_f32_32x32x16_bf16 v[34:49], v[234:237], v[74:77], v[34:49]
	s_waitcnt lgkmcnt(5)
	v_mfma_f32_32x32x16_bf16 v[82:97], v[180:183], v[138:141], v[82:97]
	ds_read_b128 v[180:183], v176 offset:32768
	v_mfma_f32_32x32x16_bf16 v[18:33], v[230:233], v[74:77], v[18:33]
	s_waitcnt lgkmcnt(5)
	v_mfma_f32_32x32x16_bf16 v[82:97], v[184:187], v[142:145], v[82:97]
	ds_read_b128 v[184:187], v177 offset:32768
	v_mfma_f32_32x32x16_bf16 v[2:17], v[226:229], v[74:77], v[2:17]
	ds_read_b64_tr_b16 v[158:159], v188 offset:0x6000
	ds_read_b64_tr_b16 v[160:161], v189 offset:0x6000
	s_waitcnt lgkmcnt(7)
	v_mfma_f32_32x32x16_bf16 v[66:81], v[146:149], v[98:101], v[210:225]
	ds_read_b128 v[146:149], v178 offset:32768
	ds_read_b64_tr_b16 v[154:155], v192 offset:0x6000
	ds_read_b64_tr_b16 v[156:157], v193 offset:0x6000
	s_waitcnt lgkmcnt(9)
	v_mfma_f32_32x32x16_bf16 v[66:81], v[150:153], v[102:105], v[66:81]
	ds_read_b128 v[150:153], v179 offset:32768
	s_waitcnt lgkmcnt(9)
	v_mfma_f32_32x32x16_bf16 v[66:81], v[246:249], v[106:109], v[66:81]
	ds_read_b128 v[246:249], v199 offset:28672
	v_exp_f32_e32 v82, v82
	v_exp_f32_e32 v83, v83
	v_exp_f32_e32 v84, v84
	v_add_f32_e32 v173, v173, v82
	s_waitcnt lgkmcnt(9)
	v_mfma_f32_32x32x16_bf16 v[66:81], v[250:253], v[110:113], v[66:81]
	ds_read_b128 v[250:253], v202 offset:28672
	v_exp_f32_e32 v85, v85
	v_mov_b32_e32 v242, v83
	v_cvt_pk_bf16_f32 v82, v82, v83
	v_exp_f32_e32 v86, v86
	s_waitcnt lgkmcnt(9)
	v_mfma_f32_32x32x16_bf16 v[66:81], v[180:183], v[122:125], v[66:81]
	ds_read_b128 v[180:183], v207 offset:28672
	v_add_f32_e32 v173, v173, v84
	v_exp_f32_e32 v87, v87
	v_add_f32_e32 v242, v242, v85
	v_cvt_pk_bf16_f32 v83, v84, v85
	s_waitcnt lgkmcnt(9)
	v_mfma_f32_32x32x16_bf16 v[66:81], v[184:187], v[114:117], v[66:81]
	ds_read_b128 v[184:187], v208 offset:28672
	ds_read_b64_tr_b16 v[238:239], v188 offset:0x7000
	ds_read_b64_tr_b16 v[240:241], v189 offset:0x7000
	v_exp_f32_e32 v88, v88
	v_add_f32_e32 v173, v173, v86
	v_exp_f32_e32 v89, v89
	v_add_f32_e32 v242, v242, v87
	s_waitcnt lgkmcnt(9)
	v_mfma_f32_32x32x16_bf16 v[66:81], v[146:149], v[118:121], v[66:81]
	ds_read_b64_tr_b16 v[234:235], v192 offset:0x7000
	ds_read_b64_tr_b16 v[236:237], v193 offset:0x7000
	v_cvt_pk_bf16_f32 v84, v86, v87
	v_add_f32_e32 v173, v173, v88
	v_add_f32_e32 v242, v242, v89
	v_cvt_pk_bf16_f32 v85, v88, v89
	s_waitcnt lgkmcnt(8)
	v_mfma_f32_32x32x16_bf16 v[66:81], v[150:153], v[126:129], v[66:81]
	ds_read_b64_tr_b16 v[230:231], v194 offset:0x7000
	ds_read_b64_tr_b16 v[232:233], v195 offset:0x7000
	ds_read_b64_tr_b16 v[150:151], v194 offset:0x6000
	ds_read_b64_tr_b16 v[152:153], v195 offset:0x6000
	ds_read_b64_tr_b16 v[146:147], v196 offset:0x6000
	ds_read_b64_tr_b16 v[148:149], v197 offset:0x6000
	v_exp_f32_e32 v90, v90
	v_exp_f32_e32 v91, v91
	v_exp_f32_e32 v92, v92
	v_add_f32_e32 v173, v173, v90
	s_waitcnt lgkmcnt(13)
	v_mfma_f32_32x32x16_bf16 v[66:81], v[246:249], v[130:133], v[66:81]
	ds_read_b64_tr_b16 v[226:227], v196 offset:0x7000
	ds_read_b64_tr_b16 v[228:229], v197 offset:0x7000
	v_exp_f32_e32 v93, v93
	v_add_f32_e32 v242, v242, v91
	v_cvt_pk_bf16_f32 v90, v90, v91
	v_exp_f32_e32 v94, v94
	s_waitcnt lgkmcnt(14)
	v_mfma_f32_32x32x16_bf16 v[66:81], v[250:253], v[134:137], v[66:81]
	v_add_f32_e32 v173, v173, v92
	v_exp_f32_e32 v95, v95
	v_add_f32_e32 v242, v242, v93
	v_cvt_pk_bf16_f32 v91, v92, v93
	s_waitcnt lgkmcnt(13)
	v_mfma_f32_32x32x16_bf16 v[66:81], v[180:183], v[138:141], v[66:81]
	v_exp_f32_e32 v96, v96
	v_add_f32_e32 v173, v173, v94
	v_exp_f32_e32 v97, v97
	v_add_f32_e32 v242, v242, v95
	s_waitcnt lgkmcnt(12)
	v_mfma_f32_32x32x16_bf16 v[66:81], v[184:187], v[142:145], v[66:81]
	v_cvt_pk_bf16_f32 v92, v94, v95
	v_add_f32_e32 v173, v173, v96
	v_add_f32_e32 v242, v242, v97
	v_cvt_pk_bf16_f32 v93, v96, v97
	s_waitcnt lgkmcnt(2)
	v_mfma_f32_32x32x16_bf16 v[50:65], v[158:161], v[82:85], v[50:65]
	ds_read_b64_tr_b16 v[158:159], v188 offset:0x8000
	ds_read_b64_tr_b16 v[160:161], v189 offset:0x8000
	v_mfma_f32_32x32x16_bf16 v[34:49], v[154:157], v[82:85], v[34:49]
	ds_read_b64_tr_b16 v[154:155], v192 offset:0x8000
	ds_read_b64_tr_b16 v[156:157], v193 offset:0x8000
	v_mfma_f32_32x32x16_bf16 v[18:33], v[150:153], v[82:85], v[18:33]
	ds_read_b64_tr_b16 v[150:151], v194 offset:0x8000
	ds_read_b64_tr_b16 v[152:153], v195 offset:0x8000
	v_mfma_f32_32x32x16_bf16 v[2:17], v[146:149], v[82:85], v[2:17]
	v_exp_f32_e32 v66, v66
	v_exp_f32_e32 v67, v67
	v_exp_f32_e32 v68, v68
	v_add_f32_e32 v173, v173, v66
	ds_read_b64_tr_b16 v[146:147], v196 offset:0x8000
	ds_read_b64_tr_b16 v[148:149], v197 offset:0x8000
	s_waitcnt lgkmcnt(8)
	v_mfma_f32_32x32x16_bf16 v[50:65], v[238:241], v[90:93], v[50:65]
	v_exp_f32_e32 v69, v69
	v_add_f32_e32 v242, v242, v67
	v_cvt_pk_bf16_f32 v66, v66, v67
	v_exp_f32_e32 v70, v70
	ds_read_b64_tr_b16 v[238:239], v188 offset:0x9000
	ds_read_b64_tr_b16 v[240:241], v189 offset:0x9000
	v_mfma_f32_32x32x16_bf16 v[34:49], v[234:237], v[90:93], v[34:49]
	v_add_f32_e32 v173, v173, v68
	v_exp_f32_e32 v71, v71
	v_add_f32_e32 v242, v242, v69
	v_cvt_pk_bf16_f32 v67, v68, v69
	ds_read_b64_tr_b16 v[234:235], v192 offset:0x9000
	ds_read_b64_tr_b16 v[236:237], v193 offset:0x9000
	v_mfma_f32_32x32x16_bf16 v[18:33], v[230:233], v[90:93], v[18:33]
	v_exp_f32_e32 v72, v72
	v_add_f32_e32 v173, v173, v70
	v_exp_f32_e32 v73, v73
	v_add_f32_e32 v242, v242, v71
	ds_read_b64_tr_b16 v[230:231], v194 offset:0x9000
	ds_read_b64_tr_b16 v[232:233], v195 offset:0x9000
	v_mfma_f32_32x32x16_bf16 v[2:17], v[226:229], v[90:93], v[2:17]
	v_cvt_pk_bf16_f32 v68, v70, v71
	v_add_f32_e32 v173, v173, v72
	v_add_f32_e32 v242, v242, v73
	v_cvt_pk_bf16_f32 v69, v72, v73
	ds_read_b64_tr_b16 v[226:227], v196 offset:0x9000
	ds_read_b64_tr_b16 v[228:229], v197 offset:0x9000
	s_waitcnt lgkmcnt(8)
	v_mfma_f32_32x32x16_bf16 v[50:65], v[158:161], v[66:69], v[50:65]
	v_mfma_f32_32x32x16_bf16 v[34:49], v[154:157], v[66:69], v[34:49]
	v_mfma_f32_32x32x16_bf16 v[18:33], v[150:153], v[66:69], v[18:33]
	v_mfma_f32_32x32x16_bf16 v[2:17], v[146:149], v[66:69], v[2:17]
	s_branch .Lu883
.Lu_pa_only:
	s_cmp_lg_u32 s57, s75
	s_cbranch_scc1 .Lu883
	v_exp_f32_e32 v74, v74
	v_exp_f32_e32 v75, v75
	v_exp_f32_e32 v76, v76
	v_add_f32_e32 v173, v173, v74
	v_exp_f32_e32 v77, v77
	v_add_f32_e32 v242, v242, v75
	v_cvt_pk_bf16_f32 v74, v74, v75
	v_exp_f32_e32 v78, v78
	v_add_f32_e32 v173, v173, v76
	v_exp_f32_e32 v79, v79
	v_add_f32_e32 v242, v242, v77
	v_cvt_pk_bf16_f32 v75, v76, v77
	v_exp_f32_e32 v80, v80
	v_add_f32_e32 v173, v173, v78
	v_exp_f32_e32 v81, v81
	v_add_f32_e32 v242, v242, v79
	v_cvt_pk_bf16_f32 v76, v78, v79
	v_add_f32_e32 v173, v173, v80
	v_add_f32_e32 v242, v242, v81
	v_cvt_pk_bf16_f32 v77, v80, v81
	v_add_f32_e32 v173, v173, v242
	s_nop 0
	v_mfma_f32_32x32x16_bf16 v[50:65], v[238:241], v[74:77], v[50:65]
	v_mfma_f32_32x32x16_bf16 v[34:49], v[234:237], v[74:77], v[34:49]
	v_mfma_f32_32x32x16_bf16 v[18:33], v[230:233], v[74:77], v[18:33]
	v_mfma_f32_32x32x16_bf16 v[2:17], v[226:229], v[74:77], v[2:17]
	s_branch .Lu883
.Lu_exit:
	s_add_i32 s98, s75, 2
	s_cmp_ge_u32 s57, s98
	s_cbranch_scc1 .LBB0_893
	v_exp_f32_e32 v74, v74
	v_exp_f32_e32 v75, v75
	v_exp_f32_e32 v76, v76
	v_add_f32_e32 v173, v173, v74
	v_exp_f32_e32 v77, v77
	v_add_f32_e32 v242, v242, v75
	v_cvt_pk_bf16_f32 v74, v74, v75
	v_exp_f32_e32 v78, v78
	v_add_f32_e32 v173, v173, v76
	v_exp_f32_e32 v79, v79
	v_add_f32_e32 v242, v242, v77
	v_cvt_pk_bf16_f32 v75, v76, v77
	v_exp_f32_e32 v80, v80
	v_add_f32_e32 v173, v173, v78
	v_exp_f32_e32 v81, v81
	v_add_f32_e32 v242, v242, v79
	v_cvt_pk_bf16_f32 v76, v78, v79
	v_add_f32_e32 v173, v173, v80
	v_add_f32_e32 v242, v242, v81
	v_cvt_pk_bf16_f32 v77, v80, v81
	v_add_f32_e32 v173, v173, v242
	s_nop 0
	v_mfma_f32_32x32x16_bf16 v[50:65], v[238:241], v[74:77], v[50:65]
	v_mfma_f32_32x32x16_bf16 v[34:49], v[234:237], v[74:77], v[34:49]
	v_mfma_f32_32x32x16_bf16 v[18:33], v[230:233], v[74:77], v[18:33]
	v_mfma_f32_32x32x16_bf16 v[2:17], v[226:229], v[74:77], v[2:17]
	s_nop 7
	s_nop 3
	s_branch .LBB0_893
